# v23 plus: lru_conv main loop software-pipelined, the next iteration's two main-row loads are issued one iteration ahead into dedicated registers
# baseline (speedup 1.0000x reference)
; #define INP(i) ((const float*)(const GASP float*)kargs()[(i)])
; __device__ __forceinline__ void lru_conv(const Frame& F, int j) {
;     ...
;     const int nrt = F.NT / 320;
;     if (F.gt >= nrt * 320) return;
;     const int c8 = (F.gt % 320) * 8, r0 = F.gt / 320;
;     const float* cw = INP(I_CONVW) + (size_t)j * 4 * DRNN + c8; const float* cb = INP(I_CONVB) + (size_t)j * DRNN + c8;
;     float w0[8], w1[8], w2[8], w3[8], bs[8];
; #pragma unroll
;     for (int e = 0; e < 8; ++e) { w0[e] = cw[e]; w1[e] = cw[DRNN + e]; w2[e] = cw[2 * DRNN + e]; w3[e] = cw[3 * DRNN + e]; bs[e] = cb[e]; }
;     for (int rowa = r0; rowa < TT; rowa += 2 * nrt) { u32x4 raw[2][4];
; #pragma unroll
;         for (int p = 0; p < 2; ++p) { const int row = rowa + p * nrt < TT ? rowa + p * nrt : rowa; const u32x4 z = (u32x4){0u, 0u, 0u, 0u}; const int t = row & 2047; const bool pr = row < TP;
;             raw[p][3] = *(const u32x4*)(XR + (size_t)row * DRNN + c8);
;             raw[p][2] = (pr && t >= 1) ? *(const u32x4*)(XR + (size_t)(row - 1) * DRNN + c8) : z; raw[p][1] = (pr && t >= 2) ? *(const u32x4*)(XR + (size_t)(row - 2) * DRNN + c8) : z; raw[p][0] = (pr && t >= 3) ? *(const u32x4*)(XR + (size_t)(row - 3) * DRNN + c8) : z; }
.LBB0_645:
	s_lshl_b32 s11, s11, 9
	v_readlane_b32 s12, v247, 17
	s_lshl_b32 s6, s6, 9
	s_add_i32 s11, s11, s12
	s_mul_hi_i32 s6, s6, 0x66666667
	v_add_u32_e32 v0, s11, v0
	s_lshr_b32 s11, s6, 31
	s_ashr_i32 s6, s6, 7
	s_add_i32 s6, s6, s11
	s_mul_i32 s11, s6, 0x140
	s_mov_b64 s[12:13], s[0:1]
	s_mov_b64 s[28:29], s[0:1]
	s_mov_b64 s[36:37], s[0:1]
	v_cmp_gt_i32_e32 vcc, s11, v0
	s_and_saveexec_b64 s[26:27], vcc
	s_cbranch_execz .LBB0_675
	s_mov_b32 s11, 0x28a000
	s_mov_b64 s[40:41], s[0:1]
	s_mov_b64 s[22:23], s[0:1]
	v_cmp_gt_i32_e32 vcc, s11, v0
	s_and_b64 exec, exec, vcc
	s_cbranch_execz .LBB0_675
	s_load_dwordx2 s[12:13], s[28:29], 0x138
	s_load_dwordx2 s[16:17], s[36:37], 0x138
	v_mul_hi_i32 v1, v0, s20
	s_load_dwordx2 s[20:21], s[22:23], 0xf8
	v_readlane_b32 s11, v246, 15
	v_lshrrev_b32_e32 v2, 31, v1
	v_ashrrev_i32_e32 v1, 7, v1
	s_load_dwordx2 s[18:19], s[40:41], 0xf0
	s_waitcnt lgkmcnt(0)
	s_add_u32 s20, s20, s11
	v_readlane_b32 s11, v246, 14
	s_addc_u32 s21, s21, s11
	s_waitcnt vmcnt(0)
	v_add_u32_e32 v110, v1, v2
	s_add_u32 s28, s12, 0x51820000
	v_mul_i32_i24_e32 v1, 0x140, v110
	s_addc_u32 s29, s13, 0
	v_sub_u32_e32 v0, v0, v1
	s_add_u32 s36, s16, 0x5bd20000
	v_lshlrev_b32_e32 v60, 3, v0
	s_addc_u32 s37, s17, 0
	v_readlane_b32 s11, v246, 13
	v_ashrrev_i32_e32 v61, 31, v60
	s_add_u32 s12, s18, s11
	v_readlane_b32 s11, v246, 12
	v_lshlrev_b64 v[62:63], 2, v[60:61]
	s_addc_u32 s13, s19, s11
	v_lshl_add_u64 v[36:37], s[12:13], 0, v[62:63]
	s_movk_i32 s11, 0x7000
	s_mov_b64 s[12:13], 0x7800
	v_add_co_u32_e32 v10, vcc, s11, v36
	v_lshl_add_u64 v[4:5], s[20:21], 0, v[62:63]
	v_lshl_add_u64 v[8:9], v[36:37], 0, s[12:13]
	v_addc_co_u32_e32 v11, vcc, 0, v37, vcc
	s_movk_i32 s11, 0x5000
	global_load_dwordx4 v[0:3], v[4:5], off
	s_nop 0
	global_load_dwordx4 v[4:7], v[4:5], off offset:16
	s_nop 0
	global_load_dwordx4 v[24:27], v[10:11], off offset:2048
	global_load_dwordx4 v[28:31], v[8:9], off offset:16
	v_add_co_u32_e32 v8, vcc, s11, v36
	s_mov_b64 s[12:13], 0x5000
	s_nop 0
	v_addc_co_u32_e32 v9, vcc, 0, v37, vcc
	v_lshl_add_u64 v[12:13], v[36:37], 0, s[12:13]
	s_mov_b64 s[12:13], 0x2800
	v_add_co_u32_e32 v16, vcc, s89, v36
	v_lshl_add_u64 v[20:21], v[36:37], 0, s[12:13]
	s_nop 0
	v_addc_co_u32_e32 v17, vcc, 0, v37, vcc
	global_load_dwordx4 v[8:11], v[8:9], off
	s_nop 0
	global_load_dwordx4 v[12:15], v[12:13], off offset:16
	s_nop 0
	global_load_dwordx4 v[16:19], v[16:17], off offset:2048
	s_nop 0
	global_load_dwordx4 v[20:23], v[20:21], off offset:16
	s_nop 0
	global_load_dwordx4 v[32:35], v[36:37], off
	s_nop 0
	global_load_dwordx4 v[36:39], v[36:37], off offset:16
	v_lshlrev_b64 v[40:41], 1, v[60:61]
	s_lshl_b32 s11, s6, 1
	v_readlane_b32 s12, v247, 58
	s_mov_b32 s20, 0x66666667
	s_mov_b32 s21, 0x48000
	v_lshl_add_u64 v[64:65], s[28:29], 0, v[40:41]
	v_lshl_add_u64 v[66:67], s[36:37], 0, v[40:41]
	s_add_i32 s12, s12, s6
	v_mad_i64_i32 v[84:85], s[16:17], v110, s91, v[40:41]
	s_mul_i32 s46, s6, 0x2800
	s_mul_hi_i32 s47, s11, 0x1400
	s_mov_b64 s[48:49], 0
	v_lshl_add_u64 v[124:125], s[28:29], 0, v[84:85]
	global_load_dwordx4 v[124:127], v[124:125], off
	v_add_u32_e32 v131, s6, v110
	s_movk_i32 s98, 0x2080
	v_cmp_gt_i32_e64 s[100:101], s98, v131
	s_nop 1
	v_cndmask_b32_e64 v131, v110, v131, s[100:101]
	v_mad_i64_i32 v[128:129], s[100:101], v131, s91, v[64:65]
	global_load_dwordx4 v[128:131], v[128:129], off
	s_waitcnt vmcnt(0)
	v_mov_b32_e32 v76, v26
	v_mov_b32_e32 v68, v30
	v_mov_b32_e32 v72, v28
	v_mov_b32_e32 v80, v24
	v_mov_b32_e32 v79, v18
	v_mov_b32_e32 v71, v22
	v_mov_b32_e32 v69, v14
	v_mov_b32_e32 v14, v31
	v_mov_b32_e32 v70, v38
	v_mov_b32_e32 v22, v39
	v_mov_b32_e32 v73, v12
	v_mov_b32_e32 v12, v29
	v_mov_b32_e32 v74, v36
	v_mov_b32_e32 v75, v20
	v_mov_b32_e32 v20, v37
	v_mov_b32_e32 v77, v10
	v_mov_b32_e32 v10, v27
	v_mov_b32_e32 v78, v34
	v_mov_b32_e32 v18, v35
	v_mov_b32_e32 v81, v8
	v_mov_b32_e32 v8, v25
	v_mov_b32_e32 v82, v32
	v_mov_b32_e32 v83, v16
	v_mov_b32_e32 v16, v33
	s_branch .LBB0_651

; __device__ __forceinline__ void lru_conv(const Frame& F, int j) {
;     ...
;     for (int rowa = r0; rowa < TT; rowa += 2 * nrt) { u32x4 raw[2][4];
; #pragma unroll
;         for (int p = 0; p < 2; ++p) { const int row = rowa + p * nrt < TT ? rowa + p * nrt : rowa; const u32x4 z = (u32x4){0u, 0u, 0u, 0u}; const int t = row & 2047; const bool pr = row < TP;
;             raw[p][3] = *(const u32x4*)(XR + (size_t)row * DRNN + c8);
;             raw[p][2] = (pr && t >= 1) ? *(const u32x4*)(XR + (size_t)(row - 1) * DRNN + c8) : z; raw[p][1] = (pr && t >= 2) ? *(const u32x4*)(XR + (size_t)(row - 2) * DRNN + c8) : z; raw[p][0] = (pr && t >= 3) ? *(const u32x4*)(XR + (size_t)(row - 3) * DRNN + c8) : z; }
.LBB0_651:
	s_waitcnt vmcnt(1)
	v_mov_b32_e32 v40, v124
	v_mov_b32_e32 v41, v125
	v_mov_b32_e32 v42, v126
	v_mov_b32_e32 v43, v127
	v_mov_b32_e32 v36, v128
	v_mov_b32_e32 v37, v129
	v_mov_b32_e32 v38, v130
	v_mov_b32_e32 v39, v131
	v_and_b32_e32 v112, 0x7ff, v110
	s_movk_i32 s13, 0x1fff
	v_cmp_gt_i32_e64 s[40:41], s89, v110
	v_cmp_ne_u32_e64 s[42:43], 0, v112
	v_cmp_lt_i32_e32 vcc, s13, v110
	v_mov_b32_e32 v48, 0
	s_and_b64 s[16:17], s[40:41], s[42:43]
	v_mov_b32_e32 v52, 0
	v_mov_b32_e32 v53, 0
	v_mov_b32_e32 v54, 0
	v_mov_b32_e32 v55, 0
	s_and_saveexec_b64 s[22:23], s[16:17]
	s_cbranch_execz .LBB0_653
	v_add_u32_e32 v24, -1, v110
	v_mad_i64_i32 v[24:25], s[16:17], v24, s91, v[64:65]
	global_load_dwordx4 v[52:55], v[24:25], off

; __device__ __forceinline__ void lru_conv(const Frame& F, int j) {
;     ...
;         for (int p = 0; p < 2; ++p) { const int row = rowa + p * nrt < TT ? rowa + p * nrt : rowa; const u32x4 z = (u32x4){0u, 0u, 0u, 0u}; const int t = row & 2047; const bool pr = row < TP;
;             raw[p][3] = *(const u32x4*)(XR + (size_t)row * DRNN + c8);
;             raw[p][2] = (pr && t >= 1) ? *(const u32x4*)(XR + (size_t)(row - 1) * DRNN + c8) : z; raw[p][1] = (pr && t >= 2) ? *(const u32x4*)(XR + (size_t)(row - 2) * DRNN + c8) : z; raw[p][0] = (pr && t >= 3) ? *(const u32x4*)(XR + (size_t)(row - 3) * DRNN + c8) : z; }
.LBB0_657:
	s_or_b64 exec, exec, s[22:23]
	v_add_u32_e32 v111, s6, v110
	s_movk_i32 s15, 0x2080
	v_cmp_gt_i32_e64 s[40:41], s15, v111
	v_mov_b32_e32 v25, 0
	s_nop 0
	v_cndmask_b32_e64 v44, v110, v111, s[40:41]
	v_and_b32_e32 v29, 0x7ff, v44
	v_cmp_gt_i32_e64 s[42:43], s89, v44
	v_cmp_ne_u32_e64 s[44:45], 0, v29
	s_and_b64 s[16:17], s[42:43], s[44:45]
	v_mov_b32_e32 v26, 0
	v_mov_b32_e32 v27, 0
	s_and_saveexec_b64 s[22:23], s[16:17]
	s_cbranch_execz .LBB0_659
	v_add_u32_e32 v24, -1, v44
	v_mad_i64_i32 v[24:25], s[16:17], v24, s91, v[64:65]
	global_load_dwordx4 v[24:27], v[24:25], off

; #define INP(i) ((const float*)(const GASP float*)kargs()[(i)])
; #define OUTP ((float*)(GASP float*)kargs()[N_IN])
; __device__ __forceinline__ void unpack8(const u32x4 w, float (&x)[8]) { x[0] = bflo(w.x); x[1] = bfhi(w.x); x[2] = bflo(w.y); x[3] = bfhi(w.y); x[4] = bflo(w.z); x[5] = bfhi(w.z); x[6] = bflo(w.w); x[7] = bfhi(w.w); }
; __device__ __forceinline__ void lru_conv(const Frame& F, int j) {
;     ...
;     for (int rowa = r0; rowa < TT; rowa += 2 * nrt) { u32x4 raw[2][4];
; #pragma unroll
;         for (int p = 0; p < 2; ++p) { const int row = rowa + p * nrt < TT ? rowa + p * nrt : rowa; const u32x4 z = (u32x4){0u, 0u, 0u, 0u}; const int t = row & 2047; const bool pr = row < TP;
;             raw[p][3] = *(const u32x4*)(XR + (size_t)row * DRNN + c8);
;             raw[p][2] = (pr && t >= 1) ? *(const u32x4*)(XR + (size_t)(row - 1) * DRNN + c8) : z; raw[p][1] = (pr && t >= 2) ? *(const u32x4*)(XR + (size_t)(row - 2) * DRNN + c8) : z; raw[p][0] = (pr && t >= 3) ? *(const u32x4*)(XR + (size_t)(row - 3) * DRNN + c8) : z; }
; #pragma unroll
;         for (int p = 0; p < 2; ++p) { const int row = rowa + p * nrt; if (row < TT) {
;         float x0[8], x1[8], x2[8], x3[8]; unpack8(raw[p][3], x3); unpack8(raw[p][2], x2); unpack8(raw[p][1], x1); unpack8(raw[p][0], x0);
;         if (row < TP) { const int t = row & 2047, b = row >> 11;
;             if (t >= 2045) { float* op = OUTP + O_PCONV + (size_t)((j * 4 + b) * 3 + (t - 2045)) * DRNN + c8; *(f32x4*)op = (f32x4){x3[0], x3[1], x3[2], x3[3]}; *(f32x4*)(op + 4) = (f32x4){x3[4], x3[5], x3[6], x3[7]}; }
;         } else { const int b = row - TP; const float* cbuf = INP(I_CONV) + (size_t)(j * 128 + b) * 3 * DRNN + c8; float* ob = OUTP + O_SCONV + (size_t)(j * 128 + b) * 3 * DRNN + c8;
; #pragma unroll
;             for (int e = 0; e < 8; ++e) { x0[e] = cbuf[e]; x1[e] = cbuf[DRNN + e]; x2[e] = cbuf[2 * DRNN + e]; ob[e] = x1[e]; ob[DRNN + e] = x2[e]; ob[2 * DRNN + e] = x3[e]; } }
.LBB0_663:
	s_or_b64 exec, exec, s[22:23]
	v_lshl_add_u64 v[124:125], s[28:29], 0, v[84:85]
	v_lshl_add_u64 v[124:125], v[124:125], 0, s[46:47]
	global_load_dwordx4 v[124:127], v[124:125], off
	v_add_u32_e32 v130, s11, v110
	v_add_u32_e32 v131, s6, v130
	v_cmp_gt_i32_e64 s[100:101], s15, v131
	s_nop 1
	v_cndmask_b32_e64 v131, v130, v131, s[100:101]
	v_mad_i64_i32 v[128:129], s[100:101], v131, s91, v[64:65]
	global_load_dwordx4 v[128:131], v[128:129], off
	s_waitcnt vmcnt(2)
	v_lshlrev_b32_e32 v44, 16, v40
	v_and_b32_e32 v92, 0xffff0000, v40
	v_lshlrev_b32_e32 v46, 16, v41
	v_and_b32_e32 v90, 0xffff0000, v41
	v_lshlrev_b32_e32 v40, 16, v42
	v_and_b32_e32 v88, 0xffff0000, v42
	v_lshlrev_b32_e32 v42, 16, v43
	v_and_b32_e32 v86, 0xffff0000, v43
	s_and_saveexec_b64 s[16:17], vcc
	s_xor_b64 s[22:23], exec, s[16:17]
	s_cbranch_execz .LBB0_665
	s_mov_b64 s[16:17], s[0:1]
	s_load_dwordx2 s[16:17], s[16:17], 0x30
	v_readlane_b32 s15, v247, 58
	s_waitcnt lgkmcnt(0)
	v_mov_b64_e32 v[48:49], s[16:17]
	v_add_u32_e32 v41, s15, v110
	s_movk_i32 s15, 0x7800
	v_mad_u64_u32 v[48:49], s[16:17], v41, s15, v[48:49]
	v_lshl_add_u64 v[48:49], v[48:49], 0, v[62:63]
	v_add_co_u32_e32 v52, vcc, s89, v48
	s_mov_b64 s[16:17], s[0:1]
	s_nop 0
	v_addc_co_u32_e32 v53, vcc, 0, v49, vcc
	global_load_dword v94, v[48:49], off
	global_load_dword v95, v[52:53], off offset:2048
	v_add_co_u32_e32 v54, vcc, s13, v48
	s_load_dwordx2 s[16:17], s[16:17], 0x130
	s_nop 0
	v_addc_co_u32_e32 v55, vcc, 0, v49, vcc
	global_load_dword v45, v[54:55], off
	s_mov_b32 s13, 0xd010000
	s_waitcnt lgkmcnt(0)
	v_mov_b64_e32 v[50:51], s[16:17]
	v_mad_u64_u32 v[50:51], s[16:17], v41, s15, v[50:51]
	v_lshl_add_u64 v[56:57], v[50:51], 0, v[62:63]
	v_add_co_u32_e32 v58, vcc, s13, v56
	s_mov_b32 s13, 0xd012000
	s_nop 0
	v_addc_co_u32_e32 v59, vcc, 0, v57, vcc
	s_mov_b64 s[16:17], 0xd010000
	v_lshl_add_u64 v[50:51], v[56:57], 0, s[16:17]
	global_load_dword v96, v[48:49], off offset:4
	global_load_dword v97, v[52:53], off offset:2052
	global_load_dword v93, v[54:55], off offset:4
	global_load_dword v98, v[48:49], off offset:8
	global_load_dword v99, v[52:53], off offset:2056
	global_load_dword v47, v[54:55], off offset:8
	global_load_dword v100, v[48:49], off offset:12
	global_load_dword v101, v[52:53], off offset:2060
	global_load_dword v91, v[54:55], off offset:12
	global_load_dword v102, v[48:49], off offset:16
	global_load_dword v103, v[52:53], off offset:2064
	global_load_dword v41, v[54:55], off offset:16
	global_load_dword v104, v[48:49], off offset:20
	global_load_dword v105, v[52:53], off offset:2068
	global_load_dword v89, v[54:55], off offset:20
	global_load_dword v106, v[48:49], off offset:24
	global_load_dword v107, v[52:53], off offset:2072
	global_load_dword v43, v[54:55], off offset:24
	global_load_dword v108, v[48:49], off offset:28
	global_load_dword v109, v[52:53], off offset:2076
	global_load_dword v87, v[54:55], off offset:28
	s_waitcnt vmcnt(0)
	global_store_dword v[58:59], v95, off
	v_add_co_u32_e32 v58, vcc, s13, v56
	s_mov_b32 s13, 0xd015000
	s_nop 0
	v_addc_co_u32_e32 v59, vcc, 0, v57, vcc
	v_add_co_u32_e32 v56, vcc, s13, v56
	global_store_dword v[58:59], v45, off offset:2048
	v_addc_co_u32_e32 v57, vcc, 0, v57, vcc
	global_store_dword v[56:57], v44, off
	global_store_dword v[50:51], v97, off offset:4
	global_store_dword v[58:59], v93, off offset:2052
	global_store_dword v[56:57], v92, off offset:4
	global_store_dword v[50:51], v99, off offset:8
	global_store_dword v[58:59], v47, off offset:2056
	global_store_dword v[56:57], v46, off offset:8
	global_store_dword v[50:51], v101, off offset:12
	global_store_dword v[58:59], v91, off offset:2060
	global_store_dword v[56:57], v90, off offset:12
	global_store_dword v[50:51], v103, off offset:16
	global_store_dword v[58:59], v41, off offset:2064
	global_store_dword v[56:57], v40, off offset:16
	global_store_dword v[50:51], v105, off offset:20
	global_store_dword v[58:59], v89, off offset:2068
	global_store_dword v[56:57], v88, off offset:20
	global_store_dword v[50:51], v107, off offset:24
	global_store_dword v[58:59], v43, off offset:2072
	global_store_dword v[56:57], v42, off offset:24
	global_store_dword v[50:51], v109, off offset:28
	global_store_dword v[58:59], v87, off offset:2076
	global_store_dword v[56:57], v86, off offset:28

; __device__ __forceinline__ unsigned cvt_pk_bf16(float lo, float hi) { unsigned r; asm volatile("v_cvt_pk_bf16_f32 %0, %1, %2" : "=v"(r) : "v"(lo), "v"(hi)); return r; }
; #define INP(i) ((const float*)(const GASP float*)kargs()[(i)])
; #define OUTP ((float*)(GASP float*)kargs()[N_IN])
; __device__ __forceinline__ void unpack8(const u32x4 w, float (&x)[8]) { x[0] = bflo(w.x); x[1] = bfhi(w.x); x[2] = bflo(w.y); x[3] = bfhi(w.y); x[4] = bflo(w.z); x[5] = bfhi(w.z); x[6] = bflo(w.w); x[7] = bfhi(w.w); }
; __device__ __forceinline__ void lru_conv(const Frame& F, int j) {
;     ...
;         for (int p = 0; p < 2; ++p) { const int row = rowa + p * nrt; if (row < TT) {
;         float x0[8], x1[8], x2[8], x3[8]; unpack8(raw[p][3], x3); unpack8(raw[p][2], x2); unpack8(raw[p][1], x1); unpack8(raw[p][0], x0);
;         if (row < TP) { const int t = row & 2047, b = row >> 11;
;             if (t >= 2045) { float* op = OUTP + O_PCONV + (size_t)((j * 4 + b) * 3 + (t - 2045)) * DRNN + c8; *(f32x4*)op = (f32x4){x3[0], x3[1], x3[2], x3[3]}; *(f32x4*)(op + 4) = (f32x4){x3[4], x3[5], x3[6], x3[7]}; }
;         } else { const int b = row - TP; const float* cbuf = INP(I_CONV) + (size_t)(j * 128 + b) * 3 * DRNN + c8; float* ob = OUTP + O_SCONV + (size_t)(j * 128 + b) * 3 * DRNN + c8;
; #pragma unroll
;             for (int e = 0; e < 8; ++e) { x0[e] = cbuf[e]; x1[e] = cbuf[DRNN + e]; x2[e] = cbuf[2 * DRNN + e]; ob[e] = x1[e]; ob[DRNN + e] = x2[e]; ob[2 * DRNN + e] = x3[e]; } }
;         float xc[8];
; #pragma unroll
;         for (int e = 0; e < 8; ++e) xc[e] = bs[e] + x0[e] * w0[e] + x1[e] * w1[e] + x2[e] * w2[e] + x3[e] * w3[e];
;         u32x4 w; w.x = cvt_pk_bf16(xc[0], xc[1]); w.y = cvt_pk_bf16(xc[2], xc[3]); w.z = cvt_pk_bf16(xc[4], xc[5]); w.w = cvt_pk_bf16(xc[6], xc[7]); *(u32x4*)(XCB + (size_t)row * DRNN + c8) = w; } }
.LBB0_669:
	s_or_b64 exec, exec, s[22:23]
	v_pk_mul_f32 v[48:49], v[82:83], v[94:95]
	v_pk_mul_f32 v[44:45], v[80:81], v[44:45]
	v_add_f32_e32 v48, v0, v48
	v_add_f32_e32 v48, v48, v49
	v_add_f32_e32 v45, v45, v48
	v_add_f32_e32 v48, v44, v45
	v_pk_mul_f32 v[44:45], v[16:17], v[96:97]
	v_pk_mul_f32 v[40:41], v[72:73], v[40:41]
	v_add_f32_e32 v44, v1, v44
	v_add_f32_e32 v49, v44, v45
	v_pk_mul_f32 v[44:45], v[8:9], v[92:93]
	s_nop 0
	v_add_f32_e32 v45, v45, v49
	v_add_f32_e32 v49, v44, v45
	v_pk_mul_f32 v[44:45], v[78:79], v[98:99]
	s_nop 0
	v_add_f32_e32 v44, v2, v44
	v_add_f32_e32 v50, v44, v45
	v_pk_mul_f32 v[44:45], v[76:77], v[46:47]
	s_nop 0
	v_add_f32_e32 v45, v45, v50
	v_add_f32_e32 v46, v44, v45
	v_pk_mul_f32 v[44:45], v[18:19], v[100:101]
	s_nop 0
	v_add_f32_e32 v44, v3, v44
	v_add_f32_e32 v47, v44, v45
	v_pk_mul_f32 v[44:45], v[10:11], v[90:91]
	s_nop 0
	v_add_f32_e32 v45, v45, v47
	v_add_f32_e32 v47, v44, v45
	v_pk_mul_f32 v[44:45], v[74:75], v[102:103]
	s_nop 0
	v_add_f32_e32 v44, v4, v44
	v_add_f32_e32 v44, v44, v45
	v_add_f32_e32 v41, v41, v44
	v_add_f32_e32 v44, v40, v41
	v_pk_mul_f32 v[40:41], v[20:21], v[104:105]
	s_nop 0
	v_add_f32_e32 v40, v5, v40
	v_add_f32_e32 v45, v40, v41
	v_pk_mul_f32 v[40:41], v[12:13], v[88:89]
	s_nop 0
	v_add_f32_e32 v41, v41, v45
	v_add_f32_e32 v45, v40, v41
	v_pk_mul_f32 v[40:41], v[70:71], v[106:107]
	s_nop 0
	v_add_f32_e32 v40, v6, v40
	v_add_f32_e32 v50, v40, v41
	v_pk_mul_f32 v[40:41], v[68:69], v[42:43]
	s_nop 0
	v_add_f32_e32 v41, v41, v50
	v_add_f32_e32 v43, v40, v41
	v_pk_mul_f32 v[40:41], v[22:23], v[108:109]
	s_nop 0
	v_add_f32_e32 v40, v7, v40
	v_add_f32_e32 v42, v40, v41
	v_pk_mul_f32 v[40:41], v[14:15], v[86:87]
	s_nop 0
	v_add_f32_e32 v41, v41, v42
	v_add_f32_e32 v50, v40, v41
	v_cvt_pk_bf16_f32 v40, v48, v49
	v_cvt_pk_bf16_f32 v41, v46, v47
	v_cvt_pk_bf16_f32 v42, v44, v45
	v_lshl_add_u64 v[44:45], s[36:37], 0, v[84:85]
	v_cvt_pk_bf16_f32 v43, v43, v50
	global_store_dwordx4 v[44:45], v[40:43], off
	s_and_saveexec_b64 s[42:43], s[40:41]
	s_cbranch_execz .LBB0_650
	s_movk_i32 s13, 0x1fff
	v_lshlrev_b32_e32 v40, 16, v36
	v_and_b32_e32 v50, 0xffff0000, v36
	v_lshlrev_b32_e32 v42, 16, v37
	v_and_b32_e32 v48, 0xffff0000, v37
	v_lshlrev_b32_e32 v36, 16, v38
	v_and_b32_e32 v46, 0xffff0000, v38
	v_lshlrev_b32_e32 v38, 16, v39
	v_and_b32_e32 v44, 0xffff0000, v39
	v_cmp_lt_i32_e32 vcc, s13, v111
	s_movk_i32 s13, 0x5000
	s_and_saveexec_b64 s[16:17], vcc
	s_xor_b64 s[22:23], exec, s[16:17]
	s_cbranch_execz .LBB0_672
	s_mov_b64 s[16:17], s[0:1]
	s_load_dwordx2 s[16:17], s[16:17], 0x30
	v_add_u32_e32 v28, s12, v110
	s_movk_i32 s15, 0x7800
	s_waitcnt lgkmcnt(0)
	v_mov_b64_e32 v[24:25], s[16:17]
	v_mad_u64_u32 v[24:25], s[16:17], v28, s15, v[24:25]
	s_mov_b64 s[16:17], s[0:1]
	s_load_dwordx2 s[16:17], s[16:17], 0x130
	v_lshl_add_u64 v[24:25], v[24:25], 0, v[62:63]
	global_load_dword v52, v[24:25], off
	s_waitcnt lgkmcnt(0)
	v_mov_b64_e32 v[26:27], s[16:17]
	v_mad_u64_u32 v[26:27], s[16:17], v28, s15, v[26:27]
	v_add_co_u32_e32 v28, vcc, s89, v24
	v_lshl_add_u64 v[32:33], v[26:27], 0, v[62:63]
	s_nop 0
	v_addc_co_u32_e32 v29, vcc, 0, v25, vcc
	global_load_dword v53, v[28:29], off offset:2048
	v_add_co_u32_e32 v30, vcc, s13, v24
	s_mov_b32 s13, 0xd010000
	s_nop 0
	v_addc_co_u32_e32 v31, vcc, 0, v25, vcc
	global_load_dword v41, v[30:31], off
	v_add_co_u32_e32 v34, vcc, s13, v32
	s_mov_b32 s13, 0xd012000
	s_nop 0
	v_addc_co_u32_e32 v35, vcc, 0, v33, vcc
	s_mov_b64 s[16:17], 0xd010000
	v_lshl_add_u64 v[26:27], v[32:33], 0, s[16:17]
	global_load_dword v54, v[24:25], off offset:4
	global_load_dword v55, v[28:29], off offset:2052
	global_load_dword v51, v[30:31], off offset:4
	global_load_dword v56, v[24:25], off offset:8
	global_load_dword v57, v[28:29], off offset:2056
	global_load_dword v43, v[30:31], off offset:8
	global_load_dword v58, v[24:25], off offset:12
	global_load_dword v59, v[28:29], off offset:2060
	global_load_dword v49, v[30:31], off offset:12
	global_load_dword v86, v[24:25], off offset:16
	global_load_dword v87, v[28:29], off offset:2064
	global_load_dword v37, v[30:31], off offset:16
	global_load_dword v88, v[24:25], off offset:20
	global_load_dword v89, v[28:29], off offset:2068
	global_load_dword v47, v[30:31], off offset:20
	global_load_dword v90, v[24:25], off offset:24
	global_load_dword v91, v[28:29], off offset:2072
	global_load_dword v39, v[30:31], off offset:24
	global_load_dword v92, v[24:25], off offset:28
	global_load_dword v93, v[28:29], off offset:2076
	global_load_dword v45, v[30:31], off offset:28
	s_waitcnt vmcnt(0)
	global_store_dword v[34:35], v53, off
	v_add_co_u32_e32 v34, vcc, s13, v32
	s_mov_b32 s13, 0xd015000
	s_nop 0
	v_addc_co_u32_e32 v35, vcc, 0, v33, vcc
	v_add_co_u32_e32 v32, vcc, s13, v32
	global_store_dword v[34:35], v41, off offset:2048
	v_addc_co_u32_e32 v33, vcc, 0, v33, vcc
	global_store_dword v[32:33], v40, off
	global_store_dword v[26:27], v55, off offset:4
	global_store_dword v[34:35], v51, off offset:2052
	global_store_dword v[32:33], v50, off offset:4
	global_store_dword v[26:27], v57, off offset:8
	global_store_dword v[34:35], v43, off offset:2056
	global_store_dword v[32:33], v42, off offset:8
	global_store_dword v[26:27], v59, off offset:12
	global_store_dword v[34:35], v49, off offset:2060
	global_store_dword v[32:33], v48, off offset:12
	global_store_dword v[26:27], v87, off offset:16
	global_store_dword v[34:35], v37, off offset:2064
	global_store_dword v[32:33], v36, off offset:16
	global_store_dword v[26:27], v89, off offset:20
	global_store_dword v[34:35], v47, off offset:2068
	global_store_dword v[32:33], v46, off offset:20
	global_store_dword v[26:27], v91, off offset:24
	global_store_dword v[34:35], v39, off offset:2072
	global_store_dword v[32:33], v38, off offset:24
	global_store_dword v[26:27], v93, off offset:28
	global_store_dword v[34:35], v45, off offset:2076
	global_store_dword v[32:33], v44, off offset:28
